# v16 + rw_scan raw-input global loads issued one full iteration ahead of their staging (16 steps of latency slack instead of 8)
# speedup vs baseline: 1.0060x; 1.0060x over previous
.LBB0_767:
	s_waitcnt vmcnt(0)
	ds_read_b128 v[0:3], v90 offset:21504
	ds_read_b128 v[4:7], v90 offset:21760
	ds_read_b128 v[12:15], v90 offset:22016
	ds_read_b128 v[16:19], v90 offset:22272
	ds_read_b128 v[20:23], v90 offset:22528
	ds_read_b32 v40, v93 offset:22784
	ds_read_b128 v[24:27], v90 offset:22848
	ds_read_b128 v[28:31], v90 offset:23104
	ds_read_b128 v[32:35], v90 offset:23360
	ds_read_b128 v[36:39], v90 offset:23616
	ds_read_b128 v[42:45], v90 offset:23872
	ds_read_b32 v46, v93 offset:24128
	s_waitcnt lgkmcnt(11)
	v_pk_mul_f32 v[0:1], v[8:9], v[0:1]
	s_add_i32 s8, s8, s84
	v_pk_fma_f32 v[0:1], v[10:11], v[2:3], v[0:1]
	s_cmpk_gt_i32 s8, 0xff
	v_add_f32_e32 v0, v0, v1
	s_nop 1
	v_add_f32_dpp v0, v0, v0 quad_perm:[1,0,3,2] row_mask:0xf bank_mask:0xf bound_ctrl:1
	s_nop 1
	v_add_f32_dpp v0, v0, v0 quad_perm:[2,3,0,1] row_mask:0xf bank_mask:0xf bound_ctrl:1
	s_nop 1
	v_add_f32_dpp v0, v0, v0 row_half_mirror row_mask:0xf bank_mask:0xf bound_ctrl:1
	s_nop 1
	v_add_f32_dpp v0, v0, v0 row_mirror row_mask:0xf bank_mask:0xf bound_ctrl:1
	s_waitcnt lgkmcnt(9)
	v_pk_mul_f32 v[2:3], v[12:13], v[0:1] op_sel_hi:[1,0]
	v_pk_mul_f32 v[0:1], v[14:15], v[0:1] op_sel_hi:[1,0]
	v_pk_fma_f32 v[2:3], v[8:9], v[4:5], v[2:3]
	v_pk_fma_f32 v[0:1], v[10:11], v[6:7], v[0:1]
	s_waitcnt lgkmcnt(6)
	v_pk_fma_f32 v[60:61], v[16:17], v[40:41], v[2:3] op_sel_hi:[1,0,1]
	v_pk_fma_f32 v[62:63], v[18:19], v[40:41], v[0:1] op_sel_hi:[1,0,1]
	s_nop 0
	v_pk_mul_f32 v[0:1], v[22:23], v[62:63]
	s_nop 0
	v_pk_fma_f32 v[0:1], v[20:21], v[60:61], v[0:1]
	s_waitcnt lgkmcnt(5)
	v_pk_mul_f32 v[20:21], v[24:25], v[60:61]
	v_add_f32_e32 v41, v0, v1
	v_pk_fma_f32 v[20:21], v[26:27], v[62:63], v[20:21]
	ds_read_b128 v[0:3], v90 offset:24192
	ds_read_b128 v[4:7], v90 offset:24448
	ds_read_b128 v[8:11], v90 offset:24704
	ds_read_b128 v[12:15], v90 offset:24960
	ds_read_b128 v[16:19], v90 offset:25216
	ds_read_b32 v40, v93 offset:25472
	v_add_f32_e32 v20, v20, v21
	s_nop 1
	v_add_f32_dpp v20, v20, v20 quad_perm:[1,0,3,2] row_mask:0xf bank_mask:0xf bound_ctrl:1
	s_nop 1
	v_add_f32_dpp v20, v20, v20 quad_perm:[2,3,0,1] row_mask:0xf bank_mask:0xf bound_ctrl:1
	s_nop 1
	v_add_f32_dpp v20, v20, v20 row_half_mirror row_mask:0xf bank_mask:0xf bound_ctrl:1
	s_nop 1
	v_add_f32_dpp v20, v20, v20 row_mirror row_mask:0xf bank_mask:0xf bound_ctrl:1
	s_waitcnt lgkmcnt(9)
	v_pk_mul_f32 v[22:23], v[32:33], v[20:21] op_sel_hi:[1,0]
	v_pk_mul_f32 v[20:21], v[34:35], v[20:21] op_sel_hi:[1,0]
	v_pk_fma_f32 v[22:23], v[28:29], v[60:61], v[22:23]
	v_pk_fma_f32 v[20:21], v[30:31], v[62:63], v[20:21]
	s_waitcnt lgkmcnt(6)
	v_pk_fma_f32 v[60:61], v[36:37], v[46:47], v[22:23] op_sel_hi:[1,0,1]
	v_pk_fma_f32 v[62:63], v[38:39], v[46:47], v[20:21] op_sel_hi:[1,0,1]
	s_waitcnt lgkmcnt(5)
	v_pk_mul_f32 v[0:1], v[0:1], v[60:61]
	v_pk_mul_f32 v[20:21], v[44:45], v[62:63]
	v_pk_fma_f32 v[0:1], v[2:3], v[62:63], v[0:1]
	v_pk_fma_f32 v[20:21], v[42:43], v[60:61], v[20:21]
	v_add_f32_e32 v0, v0, v1
	v_add_f32_e32 v47, v20, v21
	ds_read_b128 v[20:23], v90 offset:25536
	ds_read_b128 v[24:27], v90 offset:25792
	ds_read_b128 v[28:31], v90 offset:26048
	ds_read_b128 v[32:35], v90 offset:26304
	ds_read_b128 v[36:39], v90 offset:26560
	ds_read_b32 v42, v93 offset:26816
	v_add_f32_dpp v0, v0, v0 quad_perm:[1,0,3,2] row_mask:0xf bank_mask:0xf bound_ctrl:1
	s_nop 1
	v_add_f32_dpp v0, v0, v0 quad_perm:[2,3,0,1] row_mask:0xf bank_mask:0xf bound_ctrl:1
	s_nop 1
	v_add_f32_dpp v0, v0, v0 row_half_mirror row_mask:0xf bank_mask:0xf bound_ctrl:1
	s_nop 1
	v_add_f32_dpp v0, v0, v0 row_mirror row_mask:0xf bank_mask:0xf bound_ctrl:1
	s_waitcnt lgkmcnt(9)
	v_pk_mul_f32 v[2:3], v[8:9], v[0:1] op_sel_hi:[1,0]
	v_pk_mul_f32 v[0:1], v[10:11], v[0:1] op_sel_hi:[1,0]
	v_pk_fma_f32 v[2:3], v[4:5], v[60:61], v[2:3]
	v_pk_fma_f32 v[0:1], v[6:7], v[62:63], v[0:1]
	s_waitcnt lgkmcnt(6)
	v_pk_fma_f32 v[44:45], v[12:13], v[40:41], v[2:3] op_sel_hi:[1,0,1]
	v_pk_fma_f32 v[60:61], v[14:15], v[40:41], v[0:1] op_sel_hi:[1,0,1]
	s_waitcnt lgkmcnt(5)
	v_pk_mul_f32 v[20:21], v[20:21], v[44:45]
	v_pk_mul_f32 v[0:1], v[18:19], v[60:61]
	v_pk_fma_f32 v[20:21], v[22:23], v[60:61], v[20:21]
	v_pk_fma_f32 v[0:1], v[16:17], v[44:45], v[0:1]
	v_add_f32_e32 v20, v20, v21
	v_add_f32_e32 v58, v0, v1
	ds_read_b128 v[0:3], v90 offset:26880
	ds_read_b128 v[4:7], v90 offset:27136
	ds_read_b128 v[8:11], v90 offset:27392
	ds_read_b128 v[12:15], v90 offset:27648
	ds_read_b128 v[16:19], v90 offset:27904
	ds_read_b32 v40, v93 offset:28160
	v_add_f32_dpp v20, v20, v20 quad_perm:[1,0,3,2] row_mask:0xf bank_mask:0xf bound_ctrl:1
	s_nop 1
	v_add_f32_dpp v20, v20, v20 quad_perm:[2,3,0,1] row_mask:0xf bank_mask:0xf bound_ctrl:1
	s_nop 1
	v_add_f32_dpp v20, v20, v20 row_half_mirror row_mask:0xf bank_mask:0xf bound_ctrl:1
	s_nop 1
	v_add_f32_dpp v20, v20, v20 row_mirror row_mask:0xf bank_mask:0xf bound_ctrl:1
	s_waitcnt lgkmcnt(9)
	v_pk_mul_f32 v[22:23], v[28:29], v[20:21] op_sel_hi:[1,0]
	v_pk_mul_f32 v[20:21], v[30:31], v[20:21] op_sel_hi:[1,0]
	v_pk_fma_f32 v[22:23], v[24:25], v[44:45], v[22:23]
	v_pk_fma_f32 v[20:21], v[26:27], v[60:61], v[20:21]
	s_waitcnt lgkmcnt(6)
	v_pk_fma_f32 v[44:45], v[32:33], v[42:43], v[22:23] op_sel_hi:[1,0,1]
	v_pk_fma_f32 v[42:43], v[34:35], v[42:43], v[20:21] op_sel_hi:[1,0,1]
	s_waitcnt lgkmcnt(5)
	v_pk_mul_f32 v[0:1], v[0:1], v[44:45]
	v_pk_mul_f32 v[20:21], v[38:39], v[42:43]
	v_pk_fma_f32 v[0:1], v[2:3], v[42:43], v[0:1]
	v_pk_fma_f32 v[20:21], v[36:37], v[44:45], v[20:21]
	v_add_f32_e32 v0, v0, v1
	v_add_f32_e32 v60, v20, v21
	ds_read_b128 v[20:23], v90 offset:28224
	ds_read_b128 v[24:27], v90 offset:28480
	ds_read_b128 v[28:31], v90 offset:28736
	ds_read_b128 v[32:35], v90 offset:28992
	ds_read_b128 v[36:39], v90 offset:29248
	ds_read_b32 v46, v93 offset:29504
	v_add_f32_dpp v0, v0, v0 quad_perm:[1,0,3,2] row_mask:0xf bank_mask:0xf bound_ctrl:1
	s_nop 1
	v_add_f32_dpp v0, v0, v0 quad_perm:[2,3,0,1] row_mask:0xf bank_mask:0xf bound_ctrl:1
	s_nop 1
	v_add_f32_dpp v0, v0, v0 row_half_mirror row_mask:0xf bank_mask:0xf bound_ctrl:1
	s_nop 1
	v_add_f32_dpp v0, v0, v0 row_mirror row_mask:0xf bank_mask:0xf bound_ctrl:1
	s_waitcnt lgkmcnt(9)
	v_pk_mul_f32 v[2:3], v[8:9], v[0:1] op_sel_hi:[1,0]
	v_pk_mul_f32 v[0:1], v[10:11], v[0:1] op_sel_hi:[1,0]
	v_pk_fma_f32 v[2:3], v[4:5], v[44:45], v[2:3]
	v_pk_fma_f32 v[0:1], v[6:7], v[42:43], v[0:1]
	s_waitcnt lgkmcnt(6)
	v_pk_fma_f32 v[44:45], v[12:13], v[40:41], v[2:3] op_sel_hi:[1,0,1]
	v_pk_fma_f32 v[42:43], v[14:15], v[40:41], v[0:1] op_sel_hi:[1,0,1]
	s_waitcnt lgkmcnt(5)
	v_pk_mul_f32 v[20:21], v[20:21], v[44:45]
	v_pk_mul_f32 v[0:1], v[18:19], v[42:43]
	v_pk_fma_f32 v[20:21], v[22:23], v[42:43], v[20:21]
	v_pk_fma_f32 v[0:1], v[16:17], v[44:45], v[0:1]
	v_add_f32_e32 v20, v20, v21
	v_add_f32_e32 v61, v0, v1
	ds_read_b128 v[16:19], v90 offset:29568
	ds_read_b128 v[8:11], v90 offset:29824
	ds_read_b128 v[12:15], v90 offset:30080
	ds_read_b128 v[4:7], v90 offset:30336
	ds_read_b128 v[0:3], v90 offset:30592
	ds_read_b32 v40, v93 offset:30848
	v_add_f32_dpp v20, v20, v20 quad_perm:[1,0,3,2] row_mask:0xf bank_mask:0xf bound_ctrl:1
	s_nop 1
	v_add_f32_dpp v20, v20, v20 quad_perm:[2,3,0,1] row_mask:0xf bank_mask:0xf bound_ctrl:1
	s_nop 1
	v_add_f32_dpp v20, v20, v20 row_half_mirror row_mask:0xf bank_mask:0xf bound_ctrl:1
	s_nop 1
	v_add_f32_dpp v20, v20, v20 row_mirror row_mask:0xf bank_mask:0xf bound_ctrl:1
	s_waitcnt lgkmcnt(9)
	v_pk_mul_f32 v[22:23], v[28:29], v[20:21] op_sel_hi:[1,0]
	v_pk_mul_f32 v[20:21], v[30:31], v[20:21] op_sel_hi:[1,0]
	v_pk_fma_f32 v[22:23], v[24:25], v[44:45], v[22:23]
	v_pk_fma_f32 v[20:21], v[26:27], v[42:43], v[20:21]
	s_waitcnt lgkmcnt(6)
	v_pk_fma_f32 v[44:45], v[32:33], v[46:47], v[22:23] op_sel_hi:[1,0,1]
	v_pk_fma_f32 v[42:43], v[34:35], v[46:47], v[20:21] op_sel_hi:[1,0,1]
	s_waitcnt lgkmcnt(5)
	v_pk_mul_f32 v[16:17], v[16:17], v[44:45]
	v_pk_mul_f32 v[20:21], v[38:39], v[42:43]
	v_pk_fma_f32 v[16:17], v[18:19], v[42:43], v[16:17]
	v_pk_fma_f32 v[20:21], v[36:37], v[44:45], v[20:21]
	v_add_f32_e32 v16, v16, v17
	v_add_f32_e32 v62, v20, v21
	ds_read_b128 v[36:39], v90 offset:30912
	ds_read_b128 v[28:31], v90 offset:31168
	ds_read_b128 v[32:35], v90 offset:31424
	ds_read_b128 v[24:27], v90 offset:31680
	ds_read_b128 v[20:23], v90 offset:31936
	ds_read_b32 v46, v93 offset:32192
	v_add_f32_dpp v16, v16, v16 quad_perm:[1,0,3,2] row_mask:0xf bank_mask:0xf bound_ctrl:1
	s_nop 1
	v_add_f32_dpp v16, v16, v16 quad_perm:[2,3,0,1] row_mask:0xf bank_mask:0xf bound_ctrl:1
	s_nop 1
	v_add_f32_dpp v16, v16, v16 row_half_mirror row_mask:0xf bank_mask:0xf bound_ctrl:1
	s_nop 1
	v_add_f32_dpp v16, v16, v16 row_mirror row_mask:0xf bank_mask:0xf bound_ctrl:1
	s_waitcnt lgkmcnt(9)
	v_pk_mul_f32 v[12:13], v[12:13], v[16:17] op_sel_hi:[1,0]
	s_nop 0
	v_pk_fma_f32 v[8:9], v[8:9], v[44:45], v[12:13]
	s_waitcnt lgkmcnt(6)
	v_pk_fma_f32 v[44:45], v[4:5], v[40:41], v[8:9] op_sel_hi:[1,0,1]
	v_pk_mul_f32 v[4:5], v[14:15], v[16:17] op_sel_hi:[1,0]
	s_waitcnt lgkmcnt(5)
	v_pk_mul_f32 v[36:37], v[36:37], v[44:45]
	v_pk_fma_f32 v[4:5], v[10:11], v[42:43], v[4:5]
	s_nop 0
	v_pk_fma_f32 v[42:43], v[6:7], v[40:41], v[4:5] op_sel_hi:[1,0,1]
	s_nop 0
	v_pk_fma_f32 v[36:37], v[38:39], v[42:43], v[36:37]
	v_pk_mul_f32 v[2:3], v[2:3], v[42:43]
	v_add_f32_e32 v36, v36, v37
	v_pk_fma_f32 v[0:1], v[0:1], v[44:45], v[2:3]
	s_nop 0
	v_add_f32_dpp v36, v36, v36 quad_perm:[1,0,3,2] row_mask:0xf bank_mask:0xf bound_ctrl:1
	v_add_f32_e32 v63, v0, v1
	ds_read_b128 v[0:3], v90 offset:32256
	ds_read_b128 v[4:7], v90 offset:32512
	ds_read_b128 v[8:11], v90 offset:32768
	ds_read_b128 v[12:15], v90 offset:33024
	ds_read_b128 v[16:19], v90 offset:33280
	ds_read_b32 v40, v93 offset:33536
	v_add_f32_dpp v36, v36, v36 quad_perm:[2,3,0,1] row_mask:0xf bank_mask:0xf bound_ctrl:1
	s_nop 1
	v_add_f32_dpp v36, v36, v36 row_half_mirror row_mask:0xf bank_mask:0xf bound_ctrl:1
	s_nop 1
	v_add_f32_dpp v36, v36, v36 row_mirror row_mask:0xf bank_mask:0xf bound_ctrl:1
	s_waitcnt lgkmcnt(9)
	v_pk_mul_f32 v[32:33], v[32:33], v[36:37] op_sel_hi:[1,0]
	s_nop 0
	v_pk_fma_f32 v[28:29], v[28:29], v[44:45], v[32:33]
	s_waitcnt lgkmcnt(6)
	v_pk_fma_f32 v[44:45], v[24:25], v[46:47], v[28:29] op_sel_hi:[1,0,1]
	v_pk_mul_f32 v[24:25], v[34:35], v[36:37] op_sel_hi:[1,0]
	s_waitcnt lgkmcnt(5)
	v_pk_mul_f32 v[0:1], v[0:1], v[44:45]
	v_pk_fma_f32 v[24:25], v[30:31], v[42:43], v[24:25]
	s_nop 0
	v_pk_fma_f32 v[42:43], v[26:27], v[46:47], v[24:25] op_sel_hi:[1,0,1]
	s_nop 0
	v_pk_fma_f32 v[0:1], v[2:3], v[42:43], v[0:1]
	v_pk_mul_f32 v[22:23], v[22:23], v[42:43]
	v_add_f32_e32 v0, v0, v1
	v_pk_fma_f32 v[20:21], v[20:21], v[44:45], v[22:23]
	s_nop 0
	v_add_f32_dpp v0, v0, v0 quad_perm:[1,0,3,2] row_mask:0xf bank_mask:0xf bound_ctrl:1
	v_add_f32_e32 v72, v20, v21
	ds_read_b128 v[20:23], v90 offset:33600
	ds_read_b128 v[24:27], v90 offset:33856
	ds_read_b128 v[28:31], v90 offset:34112
	ds_read_b128 v[32:35], v90 offset:34368
	ds_read_b128 v[36:39], v90 offset:34624
	ds_read_b32 v46, v93 offset:34880
	v_add_f32_dpp v0, v0, v0 quad_perm:[2,3,0,1] row_mask:0xf bank_mask:0xf bound_ctrl:1
	s_nop 1
	v_add_f32_dpp v0, v0, v0 row_half_mirror row_mask:0xf bank_mask:0xf bound_ctrl:1
	s_nop 1
	v_add_f32_dpp v0, v0, v0 row_mirror row_mask:0xf bank_mask:0xf bound_ctrl:1
	s_waitcnt lgkmcnt(9)
	v_pk_mul_f32 v[2:3], v[8:9], v[0:1] op_sel_hi:[1,0]
	v_pk_mul_f32 v[0:1], v[10:11], v[0:1] op_sel_hi:[1,0]
	v_pk_fma_f32 v[2:3], v[4:5], v[44:45], v[2:3]
	v_pk_fma_f32 v[0:1], v[6:7], v[42:43], v[0:1]
	s_waitcnt lgkmcnt(6)
	v_pk_fma_f32 v[44:45], v[12:13], v[40:41], v[2:3] op_sel_hi:[1,0,1]
	v_pk_fma_f32 v[42:43], v[14:15], v[40:41], v[0:1] op_sel_hi:[1,0,1]
	s_waitcnt lgkmcnt(5)
	v_pk_mul_f32 v[20:21], v[20:21], v[44:45]
	v_pk_mul_f32 v[0:1], v[18:19], v[42:43]
	v_pk_fma_f32 v[20:21], v[22:23], v[42:43], v[20:21]
	v_pk_fma_f32 v[0:1], v[16:17], v[44:45], v[0:1]
	v_add_f32_e32 v20, v20, v21
	v_add_f32_e32 v73, v0, v1
	ds_read_b128 v[0:3], v90 offset:34944
	ds_read_b128 v[4:7], v90 offset:35200
	ds_read_b128 v[8:11], v90 offset:35456
	ds_read_b128 v[12:15], v90 offset:35712
	ds_read_b128 v[16:19], v90 offset:35968
	ds_read_b32 v40, v93 offset:36224
	v_add_f32_dpp v20, v20, v20 quad_perm:[1,0,3,2] row_mask:0xf bank_mask:0xf bound_ctrl:1
	s_nop 1
	v_add_f32_dpp v20, v20, v20 quad_perm:[2,3,0,1] row_mask:0xf bank_mask:0xf bound_ctrl:1
	s_nop 1
	v_add_f32_dpp v20, v20, v20 row_half_mirror row_mask:0xf bank_mask:0xf bound_ctrl:1
	s_nop 1
	v_add_f32_dpp v20, v20, v20 row_mirror row_mask:0xf bank_mask:0xf bound_ctrl:1
	s_waitcnt lgkmcnt(9)
	v_pk_mul_f32 v[22:23], v[28:29], v[20:21] op_sel_hi:[1,0]
	v_pk_mul_f32 v[20:21], v[30:31], v[20:21] op_sel_hi:[1,0]
	v_pk_fma_f32 v[22:23], v[24:25], v[44:45], v[22:23]
	v_pk_fma_f32 v[20:21], v[26:27], v[42:43], v[20:21]
	s_waitcnt lgkmcnt(6)
	v_pk_fma_f32 v[44:45], v[32:33], v[46:47], v[22:23] op_sel_hi:[1,0,1]
	v_pk_fma_f32 v[42:43], v[34:35], v[46:47], v[20:21] op_sel_hi:[1,0,1]
	s_waitcnt lgkmcnt(5)
	v_pk_mul_f32 v[0:1], v[0:1], v[44:45]
	v_pk_mul_f32 v[20:21], v[38:39], v[42:43]
	v_pk_fma_f32 v[0:1], v[2:3], v[42:43], v[0:1]
	v_pk_fma_f32 v[20:21], v[36:37], v[44:45], v[20:21]
	v_add_f32_e32 v0, v0, v1
	v_add_f32_e32 v74, v20, v21
	ds_read_b128 v[20:23], v90 offset:36288
	ds_read_b128 v[24:27], v90 offset:36544
	ds_read_b128 v[28:31], v90 offset:36800
	ds_read_b128 v[32:35], v90 offset:37056
	ds_read_b128 v[36:39], v90 offset:37312
	ds_read_b32 v46, v93 offset:37568
	v_add_f32_dpp v0, v0, v0 quad_perm:[1,0,3,2] row_mask:0xf bank_mask:0xf bound_ctrl:1
	s_nop 1
	v_add_f32_dpp v0, v0, v0 quad_perm:[2,3,0,1] row_mask:0xf bank_mask:0xf bound_ctrl:1
	s_nop 1
	v_add_f32_dpp v0, v0, v0 row_half_mirror row_mask:0xf bank_mask:0xf bound_ctrl:1
	s_nop 1
	v_add_f32_dpp v0, v0, v0 row_mirror row_mask:0xf bank_mask:0xf bound_ctrl:1
	s_waitcnt lgkmcnt(9)
	v_pk_mul_f32 v[2:3], v[8:9], v[0:1] op_sel_hi:[1,0]
	v_pk_mul_f32 v[0:1], v[10:11], v[0:1] op_sel_hi:[1,0]
	v_pk_fma_f32 v[2:3], v[4:5], v[44:45], v[2:3]
	v_pk_fma_f32 v[0:1], v[6:7], v[42:43], v[0:1]
	s_waitcnt lgkmcnt(6)
	v_pk_fma_f32 v[44:45], v[12:13], v[40:41], v[2:3] op_sel_hi:[1,0,1]
	v_pk_fma_f32 v[42:43], v[14:15], v[40:41], v[0:1] op_sel_hi:[1,0,1]
	s_waitcnt lgkmcnt(5)
	v_pk_mul_f32 v[20:21], v[20:21], v[44:45]
	v_pk_mul_f32 v[0:1], v[18:19], v[42:43]
	v_pk_fma_f32 v[20:21], v[22:23], v[42:43], v[20:21]
	v_pk_fma_f32 v[0:1], v[16:17], v[44:45], v[0:1]
	v_add_f32_e32 v20, v20, v21
	v_add_f32_e32 v75, v0, v1
	ds_read_b128 v[0:3], v90 offset:37632
	ds_read_b128 v[4:7], v90 offset:37888
	ds_read_b128 v[8:11], v90 offset:38144
	ds_read_b128 v[12:15], v90 offset:38400
	ds_read_b128 v[16:19], v90 offset:38656
	ds_read_b32 v40, v93 offset:38912
	v_add_f32_dpp v20, v20, v20 quad_perm:[1,0,3,2] row_mask:0xf bank_mask:0xf bound_ctrl:1
	s_nop 1
	v_add_f32_dpp v20, v20, v20 quad_perm:[2,3,0,1] row_mask:0xf bank_mask:0xf bound_ctrl:1
	s_nop 1
	v_add_f32_dpp v20, v20, v20 row_half_mirror row_mask:0xf bank_mask:0xf bound_ctrl:1
	s_nop 1
	v_add_f32_dpp v20, v20, v20 row_mirror row_mask:0xf bank_mask:0xf bound_ctrl:1
	s_waitcnt lgkmcnt(9)
	v_pk_mul_f32 v[22:23], v[28:29], v[20:21] op_sel_hi:[1,0]
	v_pk_mul_f32 v[20:21], v[30:31], v[20:21] op_sel_hi:[1,0]
	v_pk_fma_f32 v[22:23], v[24:25], v[44:45], v[22:23]
	v_pk_fma_f32 v[20:21], v[26:27], v[42:43], v[20:21]
	s_waitcnt lgkmcnt(6)
	v_pk_fma_f32 v[44:45], v[32:33], v[46:47], v[22:23] op_sel_hi:[1,0,1]
	v_pk_fma_f32 v[42:43], v[34:35], v[46:47], v[20:21] op_sel_hi:[1,0,1]
	s_waitcnt lgkmcnt(5)
	v_pk_mul_f32 v[0:1], v[0:1], v[44:45]
	v_pk_mul_f32 v[20:21], v[38:39], v[42:43]
	v_pk_fma_f32 v[0:1], v[2:3], v[42:43], v[0:1]
	v_pk_fma_f32 v[20:21], v[36:37], v[44:45], v[20:21]
	v_add_f32_e32 v0, v0, v1
	v_add_f32_e32 v76, v20, v21
	ds_read_b128 v[20:23], v90 offset:38976
	ds_read_b128 v[24:27], v90 offset:39232
	ds_read_b128 v[28:31], v90 offset:39488
	ds_read_b128 v[32:35], v90 offset:39744
	ds_read_b128 v[36:39], v90 offset:40000
	ds_read_b32 v46, v93 offset:40256
	v_add_f32_dpp v0, v0, v0 quad_perm:[1,0,3,2] row_mask:0xf bank_mask:0xf bound_ctrl:1
	s_nop 1
	v_add_f32_dpp v0, v0, v0 quad_perm:[2,3,0,1] row_mask:0xf bank_mask:0xf bound_ctrl:1
	s_nop 1
	v_add_f32_dpp v0, v0, v0 row_half_mirror row_mask:0xf bank_mask:0xf bound_ctrl:1
	s_nop 1
	v_add_f32_dpp v0, v0, v0 row_mirror row_mask:0xf bank_mask:0xf bound_ctrl:1
	s_waitcnt lgkmcnt(9)
	v_pk_mul_f32 v[2:3], v[8:9], v[0:1] op_sel_hi:[1,0]
	v_pk_mul_f32 v[0:1], v[10:11], v[0:1] op_sel_hi:[1,0]
	v_pk_fma_f32 v[2:3], v[4:5], v[44:45], v[2:3]
	v_pk_fma_f32 v[0:1], v[6:7], v[42:43], v[0:1]
	s_waitcnt lgkmcnt(6)
	v_pk_fma_f32 v[44:45], v[12:13], v[40:41], v[2:3] op_sel_hi:[1,0,1]
	v_pk_fma_f32 v[42:43], v[14:15], v[40:41], v[0:1] op_sel_hi:[1,0,1]
	s_waitcnt lgkmcnt(5)
	v_pk_mul_f32 v[20:21], v[20:21], v[44:45]
	v_pk_mul_f32 v[0:1], v[18:19], v[42:43]
	v_pk_fma_f32 v[20:21], v[22:23], v[42:43], v[20:21]
	v_pk_fma_f32 v[0:1], v[16:17], v[44:45], v[0:1]
	v_add_f32_e32 v20, v20, v21
	v_add_f32_e32 v77, v0, v1
	ds_read_b128 v[16:19], v90 offset:40320
	ds_read_b128 v[8:11], v90 offset:40576
	ds_read_b128 v[12:15], v90 offset:40832
	ds_read_b128 v[4:7], v90 offset:41088
	ds_read_b128 v[0:3], v90 offset:41344
	ds_read_b32 v40, v93 offset:41600
	v_add_f32_dpp v20, v20, v20 quad_perm:[1,0,3,2] row_mask:0xf bank_mask:0xf bound_ctrl:1
	s_nop 1
	v_add_f32_dpp v20, v20, v20 quad_perm:[2,3,0,1] row_mask:0xf bank_mask:0xf bound_ctrl:1
	s_nop 1
	v_add_f32_dpp v20, v20, v20 row_half_mirror row_mask:0xf bank_mask:0xf bound_ctrl:1
	s_nop 1
	v_add_f32_dpp v20, v20, v20 row_mirror row_mask:0xf bank_mask:0xf bound_ctrl:1
	s_waitcnt lgkmcnt(9)
	v_pk_mul_f32 v[22:23], v[28:29], v[20:21] op_sel_hi:[1,0]
	v_pk_mul_f32 v[20:21], v[30:31], v[20:21] op_sel_hi:[1,0]
	v_pk_fma_f32 v[22:23], v[24:25], v[44:45], v[22:23]
	v_pk_fma_f32 v[20:21], v[26:27], v[42:43], v[20:21]
	s_waitcnt lgkmcnt(6)
	v_pk_fma_f32 v[44:45], v[32:33], v[46:47], v[22:23] op_sel_hi:[1,0,1]
	v_pk_fma_f32 v[42:43], v[34:35], v[46:47], v[20:21] op_sel_hi:[1,0,1]
	s_waitcnt lgkmcnt(5)
	v_pk_mul_f32 v[16:17], v[16:17], v[44:45]
	v_pk_mul_f32 v[20:21], v[38:39], v[42:43]
	v_pk_fma_f32 v[16:17], v[18:19], v[42:43], v[16:17]
	v_pk_fma_f32 v[20:21], v[36:37], v[44:45], v[20:21]
	v_add_f32_e32 v16, v16, v17
	v_add_f32_e32 v78, v20, v21
	ds_read_b128 v[36:39], v90 offset:41664
	ds_read_b128 v[20:23], v90 offset:41920
	ds_read_b128 v[32:35], v90 offset:42176
	ds_read_b128 v[28:31], v90 offset:42432
	ds_read_b128 v[24:27], v90 offset:42688
	ds_read_b32 v46, v93 offset:42944
	v_add_f32_dpp v16, v16, v16 quad_perm:[1,0,3,2] row_mask:0xf bank_mask:0xf bound_ctrl:1
	s_nop 1
	v_add_f32_dpp v16, v16, v16 quad_perm:[2,3,0,1] row_mask:0xf bank_mask:0xf bound_ctrl:1
	s_nop 1
	v_add_f32_dpp v16, v16, v16 row_half_mirror row_mask:0xf bank_mask:0xf bound_ctrl:1
	s_nop 1
	v_add_f32_dpp v16, v16, v16 row_mirror row_mask:0xf bank_mask:0xf bound_ctrl:1
	s_waitcnt lgkmcnt(9)
	v_pk_mul_f32 v[12:13], v[12:13], v[16:17] op_sel_hi:[1,0]
	s_nop 0
	v_pk_fma_f32 v[8:9], v[8:9], v[44:45], v[12:13]
	s_waitcnt lgkmcnt(6)
	v_pk_fma_f32 v[4:5], v[4:5], v[40:41], v[8:9] op_sel_hi:[1,0,1]
	v_pk_mul_f32 v[8:9], v[14:15], v[16:17] op_sel_hi:[1,0]
	s_nop 0
	v_pk_fma_f32 v[8:9], v[10:11], v[42:43], v[8:9]
	s_nop 0
	v_pk_fma_f32 v[6:7], v[6:7], v[40:41], v[8:9] op_sel_hi:[1,0,1]
	s_nop 0
	v_pk_mul_f32 v[2:3], v[2:3], v[6:7]
	s_nop 0
	v_pk_fma_f32 v[0:1], v[0:1], v[4:5], v[2:3]
	s_nop 0
	v_add_f32_e32 v8, v0, v1
	s_waitcnt lgkmcnt(5)
	v_pk_mul_f32 v[0:1], v[36:37], v[4:5]
	s_nop 0
	v_pk_fma_f32 v[0:1], v[38:39], v[6:7], v[0:1]
	s_nop 0
	v_add_f32_e32 v0, v0, v1
	s_nop 1
	v_add_f32_dpp v0, v0, v0 quad_perm:[1,0,3,2] row_mask:0xf bank_mask:0xf bound_ctrl:1
	s_nop 1
	v_add_f32_dpp v0, v0, v0 quad_perm:[2,3,0,1] row_mask:0xf bank_mask:0xf bound_ctrl:1
	s_nop 1
	v_add_f32_dpp v0, v0, v0 row_half_mirror row_mask:0xf bank_mask:0xf bound_ctrl:1
	s_nop 1
	v_add_f32_dpp v0, v0, v0 row_mirror row_mask:0xf bank_mask:0xf bound_ctrl:1
	s_waitcnt lgkmcnt(3)
	v_pk_mul_f32 v[2:3], v[32:33], v[0:1] op_sel_hi:[1,0]
	v_pk_mul_f32 v[0:1], v[34:35], v[0:1] op_sel_hi:[1,0]
	v_pk_fma_f32 v[2:3], v[20:21], v[4:5], v[2:3]
	v_pk_fma_f32 v[0:1], v[22:23], v[6:7], v[0:1]
	s_waitcnt lgkmcnt(0)
	v_pk_fma_f32 v[2:3], v[28:29], v[46:47], v[2:3] op_sel_hi:[1,0,1]
	v_pk_fma_f32 v[0:1], v[30:31], v[46:47], v[0:1] op_sel_hi:[1,0,1]
	v_cndmask_b32_e64 v4, v58, v75, s[38:39]
	v_pk_mul_f32 v[0:1], v[26:27], v[0:1]
	v_cndmask_b32_e64 v5, v60, v76, s[38:39]
	v_pk_fma_f32 v[0:1], v[24:25], v[2:3], v[0:1]
	v_cndmask_b32_e64 v2, v41, v73, s[38:39]
	v_add_f32_e32 v0, v0, v1
	v_cndmask_b32_e64 v1, v73, v41, s[38:39]
	v_cndmask_b32_e64 v3, v47, v74, s[38:39]
	v_cndmask_b32_e64 v6, v61, v77, s[38:39]
	v_add_f32_dpp v1, v2, v1 row_mirror row_mask:0xf bank_mask:0xf bound_ctrl:1
	v_cndmask_b32_e64 v2, v74, v47, s[38:39]
	v_cndmask_b32_e64 v7, v62, v78, s[38:39]
	s_nop 0
	v_add_f32_dpp v2, v3, v2 row_mirror row_mask:0xf bank_mask:0xf bound_ctrl:1
	v_cndmask_b32_e64 v3, v75, v58, s[38:39]
	s_nop 1
	v_add_f32_dpp v3, v4, v3 row_mirror row_mask:0xf bank_mask:0xf bound_ctrl:1
	v_cndmask_b32_e64 v4, v76, v60, s[38:39]
	s_nop 1
	v_add_f32_dpp v4, v5, v4 row_mirror row_mask:0xf bank_mask:0xf bound_ctrl:1
	v_cndmask_b32_e64 v5, v77, v61, s[38:39]
	s_nop 1
	v_add_f32_dpp v5, v6, v5 row_mirror row_mask:0xf bank_mask:0xf bound_ctrl:1
	v_cndmask_b32_e64 v6, v78, v62, s[38:39]
	s_nop 1
	v_add_f32_dpp v6, v7, v6 row_mirror row_mask:0xf bank_mask:0xf bound_ctrl:1
	v_cndmask_b32_e64 v7, v8, v63, s[38:39]
	v_cndmask_b32_e64 v8, v63, v8, s[38:39]
	s_nop 1
	v_add_f32_dpp v7, v8, v7 row_mirror row_mask:0xf bank_mask:0xf bound_ctrl:1
	v_cndmask_b32_e64 v8, v0, v72, s[38:39]
	v_cndmask_b32_e64 v0, v72, v0, s[38:39]
	s_nop 1
	v_add_f32_dpp v0, v0, v8 row_mirror row_mask:0xf bank_mask:0xf bound_ctrl:1
	v_cndmask_b32_e64 v8, v5, v1, s[40:41]
	v_cndmask_b32_e64 v1, v1, v5, s[40:41]
	v_cndmask_b32_e64 v5, v6, v2, s[40:41]
	v_cndmask_b32_e64 v2, v2, v6, s[40:41]
	v_add_f32_dpp v1, v1, v8 row_half_mirror row_mask:0xf bank_mask:0xf bound_ctrl:1
	s_nop 0
	v_add_f32_dpp v2, v2, v5 row_half_mirror row_mask:0xf bank_mask:0xf bound_ctrl:1
	v_cndmask_b32_e64 v5, v7, v3, s[40:41]
	v_cndmask_b32_e64 v3, v3, v7, s[40:41]
	s_nop 1
	v_add_f32_dpp v3, v3, v5 row_half_mirror row_mask:0xf bank_mask:0xf bound_ctrl:1
	v_cndmask_b32_e64 v5, v0, v4, s[40:41]
	v_cndmask_b32_e64 v0, v4, v0, s[40:41]
	v_cndmask_b32_e64 v4, v3, v1, s[42:43]
	v_cndmask_b32_e64 v1, v1, v3, s[42:43]
	v_add_f32_dpp v0, v0, v5 row_half_mirror row_mask:0xf bank_mask:0xf bound_ctrl:1
	v_cndmask_b32_e64 v3, v0, v2, s[42:43]
	v_cndmask_b32_e64 v0, v2, v0, s[42:43]
	v_add_f32_dpp v1, v1, v4 quad_perm:[2,3,0,1] row_mask:0xf bank_mask:0xf bound_ctrl:1
	s_nop 0
	v_add_f32_dpp v0, v0, v3 quad_perm:[2,3,0,1] row_mask:0xf bank_mask:0xf bound_ctrl:1
	v_cndmask_b32_e64 v2, v0, v1, s[44:45]
	v_cndmask_b32_e64 v0, v1, v0, s[44:45]
	s_nop 1
	v_add_f32_dpp v1, v0, v2 quad_perm:[1,0,3,2] row_mask:0xf bank_mask:0xf bound_ctrl:1
	v_cndmask_b32_e64 v0, v95, v94, s[46:47]
	v_or_b32_e32 v0, v98, v0
	v_cvt_pk_bf16_f32 v2, v1, s0
	v_ashrrev_i32_e32 v1, 31, v0
	v_lshlrev_b64 v[0:1], 11, v[0:1]
	v_lshl_add_u64 v[0:1], v[56:57], 0, v[0:1]
	global_store_short v[0:1], v2, off
	s_barrier
	s_cbranch_scc1 .LBB0_778
.LBB0_768:
	s_lshl_b32 s0, s8, 5
	s_and_b32 s0, s0, 0xe0
	s_ashr_i32 s11, s8, 3
	s_add_i32 s0, s0, s11
	s_bfe_u32 s9, s0, 0x40003
	s_lshl_b32 s6, s9, 8
	v_lshl_add_u64 v[0:1], v[52:53], 0, s[6:7]
	v_lshl_add_u64 v[4:5], v[54:55], 0, s[6:7]
	global_load_dwordx4 v[0:3], v[0:1], off
	s_bfe_u32 s6, s11, 0x10002
	global_load_dwordx4 v[4:7], v[4:5], off
	s_ashr_i32 s12, s0, 7
	s_cmp_eq_u32 s6, 0
	s_cselect_b64 s[46:47], -1, 0
	s_and_saveexec_b64 s[0:1], s[36:37]
	s_xor_b64 s[0:1], exec, s[0:1]
	v_cndmask_b32_e64 v8, v59, v51, s[46:47]
	s_lshl_b32 s10, s12, 13
	s_lshl_b32 s13, s12, 8
	v_add_u32_e32 v8, s10, v8
	v_mov_b32_e32 v10, s13
	v_mov_b32_e32 v98, s10
	s_or_saveexec_b64 s[0:1], s[0:1]
	s_lshl_b32 s10, s9, 6
	s_xor_b64 exec, exec, s[0:1]
	v_cndmask_b32_e64 v8, v71, v49, s[46:47]
	s_lshl_b32 s13, s12, 8
	v_add_u32_e32 v8, s13, v8
	s_lshl_b32 s12, s12, 13
	v_add_u32_e32 v8, 0x4000, v8
	v_mov_b32_e32 v10, s13
	v_mov_b32_e32 v98, s12
	s_or_b64 exec, exec, s[0:1]
	v_mov_b32_e32 v131, v8
	s_lshl_b32 s0, s6, 5
	s_sub_i32 s0, 16, s0
	v_mov_b32_e32 v132, s0
	v_sub_u32_e32 v133, 0x1fff, v49
	v_cndmask_b32_e64 v133, v133, v49, s[46:47]
	v_add_u32_e32 v133, v98, v133
	s_lshl_b32 s0, s9, 2
	v_mov_b32_e32 v134, s0
	s_mul_i32 s6, s6, 0x2100000
	v_ashrrev_i32_e32 v9, 31, v8
	s_add_u32 s24, s86, s6
	v_or_b32_e32 v58, s10, v50
	v_lshlrev_b64 v[12:13], 11, v[8:9]
	s_addc_u32 s25, s87, 0
	v_readlane_b32 s0, v182, 23
	v_lshl_or_b32 v14, v58, 1, v12
	v_mov_b32_e32 v15, v13
	v_readlane_b32 s1, v182, 24
	s_add_u32 s20, s0, s6
	v_lshl_add_u64 v[16:17], s[2:3], 0, v[14:15]
	v_lshl_or_b32 v8, v8, 4, s9
	s_addc_u32 s21, s1, 0
	global_load_dwordx2 v[16:17], v[16:17], off
	v_ashrrev_i32_e32 v9, 31, v8
	v_lshl_add_u64 v[18:19], s[90:91], 0, v[14:15]
	v_lshl_add_u64 v[20:21], s[20:21], 0, v[14:15]
	v_lshl_add_u64 v[14:15], s[24:25], 0, v[14:15]
	v_lshl_add_u64 v[8:9], v[8:9], 2, s[74:75]
	global_load_dwordx2 v[18:19], v[18:19], off
	s_add_u32 vcc_lo, s22, s6
	global_load_dwordx2 v[22:23], v[14:15], off
	v_readlane_b32 s12, v181, 42
	global_load_dword v8, v[8:9], off
	s_addc_u32 vcc_hi, s23, 0
	global_load_dwordx2 v[20:21], v[20:21], off
	s_lshl_b32 s0, s11, 4
	v_readlane_b32 s13, v181, 43
	s_and_b32 s11, s0, 48
	s_lshl_b32 s6, s10, 1
	v_lshl_add_u64 v[12:13], s[12:13], 0, v[12:13]
	v_lshl_add_u64 v[12:13], v[12:13], 0, s[6:7]
	s_lshl_b32 s0, s11, 1
	s_mov_b32 s1, s7
	v_lshl_add_u64 v[12:13], v[12:13], 0, s[0:1]
	v_lshl_add_u64 v[24:25], v[12:13], 0, v[68:69]
	s_add_i32 s10, s10, s11
	s_add_u32 s1, s12, s6
	s_addc_u32 s6, s13, 0
	s_add_u32 s0, s1, s0
	s_addc_u32 s1, s6, 0
	v_lshl_add_u64 v[60:61], s[0:1], 0, v[68:69]
	v_add_u32_e32 v99, 0x4000, v10
	s_mov_b32 s6, 0
	v_mov_b32_e32 v100, v97
	v_mov_b32_e32 v101, v96
	s_waitcnt vmcnt(4)
	v_lshlrev_b32_e32 v26, 16, v16
	v_and_b32_e32 v27, 0xffff0000, v16
	v_pk_mul_f32 v[12:13], v[0:1], v[26:27]
	s_waitcnt vmcnt(2)
	v_alignbit_b32 v11, v23, v22, 16
	s_waitcnt vmcnt(1)
	v_pk_mul_f32 v[30:31], v[12:13], v[8:9] op_sel_hi:[1,0]
	v_alignbit_b32 v9, v17, v16, 16
	v_and_b32_e32 v17, 0xffff0000, v17
	v_and_b32_e32 v16, 0xffff0000, v9
	v_pk_mul_f32 v[14:15], v[2:3], v[16:17]
	v_xor_b32_e32 v13, 0x80000000, v31
	v_pk_mul_f32 v[8:9], v[8:9], v[14:15] op_sel_hi:[0,1]
	v_xor_b32_e32 v12, 0x80000000, v30
	v_xor_b32_e32 v15, 0x80000000, v9
	v_xor_b32_e32 v14, 0x80000000, v8
	ds_write_b128 v81, v[12:15]
	v_lshlrev_b32_e32 v12, 16, v22
	v_and_b32_e32 v13, 0xffff0000, v22
	v_and_b32_e32 v15, 0xffff0000, v23
	v_and_b32_e32 v14, 0xffff0000, v11
	s_waitcnt vmcnt(0)
	v_alignbit_b32 v11, v21, v20, 16
	v_lshlrev_b32_e32 v28, 16, v20
	v_and_b32_e32 v29, 0xffff0000, v20
	v_pk_add_f32 v[12:13], v[12:13], 1.0 op_sel_hi:[1,0] neg_lo:[1,0] neg_hi:[1,0]
	v_pk_add_f32 v[14:15], v[14:15], 1.0 op_sel_hi:[1,0] neg_lo:[1,0] neg_hi:[1,0]
	v_and_b32_e32 v21, 0xffff0000, v21
	v_and_b32_e32 v20, 0xffff0000, v11
	ds_write_b128 v81, v[12:15] offset:256
	v_pk_mul_f32 v[14:15], v[8:9], v[20:21]
	v_pk_add_f32 v[8:9], v[28:29], -1.0 op_sel_hi:[1,0]
	v_pk_mul_f32 v[12:13], v[30:31], v[28:29]
	v_pk_fma_f32 v[8:9], v[4:5], v[8:9], 1.0 op_sel_hi:[1,1,0]
	ds_write_b128 v81, v[12:15] offset:512
	v_pk_mul_f32 v[12:13], v[8:9], v[26:27]
	v_pk_add_f32 v[8:9], v[20:21], -1.0 op_sel_hi:[1,0]
	s_nop 0
	v_pk_fma_f32 v[8:9], v[6:7], v[8:9], 1.0 op_sel_hi:[1,1,0]
	s_nop 0
	v_pk_mul_f32 v[14:15], v[8:9], v[16:17]
	v_alignbit_b32 v8, v19, v18, 16
	ds_write_b128 v81, v[12:15] offset:768
	v_and_b32_e32 v14, 0xffff0000, v8
	global_load_ushort v8, v[24:25], off
	v_and_b32_e32 v15, 0xffff0000, v19
	v_lshlrev_b32_e32 v12, 16, v18
	v_and_b32_e32 v13, 0xffff0000, v18
	ds_write_b128 v81, v[12:15] offset:1024
	s_waitcnt vmcnt(0)
	v_lshlrev_b32_e32 v8, 16, v8
	ds_write_b32 v88, v8 offset:1280
	v_add_u32_e32 v8, s10, v89
	v_ashrrev_i32_e32 v9, 31, v8
	v_lshl_add_u64 v[56:57], v[8:9], 1, vcc
	v_mov_b32_e32 v8, 0
	s_mov_b32 s10, 0
	v_mov_b32_e32 v9, v8
	v_mov_b32_e32 v10, v8
	v_mov_b32_e32 v11, v8
	v_lshlrev_b32_e32 v58, 1, v58
	v_readlane_b32 s100, v181, 42
	v_readlane_b32 s101, v181, 43
	v_sub_u32_e32 v12, 0xff, v48
	v_cndmask_b32_e64 v12, v12, v48, s[46:47]
	v_add_u32_e32 v100, v99, v12
	v_sub_u32_e32 v12, 0x1fff, v48
	v_cndmask_b32_e64 v12, v12, v48, s[46:47]
	v_add_u32_e32 v101, v98, v12
	v_subrev_u32_e32 v60, s100, v60
	v_subrev_u32_e32 v99, s100, v56
	v_add_u32_e32 v131, v132, v131
	v_lshl_add_u32 v13, v131, 11, v58
	v_lshl_add_u32 v14, v131, 6, v134
	v_lshl_add_u32 v15, v131, 11, v60
	global_load_dwordx2 v[74:75], v13, s[2:3]
	global_load_dwordx2 v[62:63], v13, s[90:91]
	global_load_dwordx2 v[76:77], v13, s[24:25]
	global_load_dword v78, v14, s[74:75]
	global_load_dwordx2 v[72:73], v13, s[20:21]
	global_load_ushort v102, v15, s[100:101]
	s_waitcnt lgkmcnt(0)
	s_barrier
	s_branch .LBB0_774
.LBB0_774:
	s_and_b32 s11, s10, 1
	s_mul_i32 s0, s11, 0x5400
	s_add_i32 s0, s0, 16
	v_lshl_add_u32 v126, v87, 2, s0
	v_add3_u32 v124, s0, v91, v92
	ds_read_b32 v204, v124 offset:1280
	ds_read_b128 v[184:187], v126 offset:0
	ds_read_b128 v[196:199], v126 offset:768
	ds_read_b128 v[188:191], v126 offset:256
	ds_read_b128 v[200:203], v126 offset:1024
	ds_read_b128 v[192:195], v126 offset:512
	ds_read_b32 v226, v124 offset:2624
	ds_read_b128 v[206:209], v126 offset:1344
	ds_read_b128 v[218:221], v126 offset:2112
	ds_read_b128 v[210:213], v126 offset:1600
	ds_read_b128 v[222:225], v126 offset:2368
	ds_read_b128 v[214:217], v126 offset:1856
	s_waitcnt lgkmcnt(6)
	v_pk_mul_f32 v[250:251], v[8:9], v[184:185]
	v_pk_mul_f32 v[252:253], v[204:205], v[196:197] op_sel_hi:[0,1]
	v_pk_fma_f32 v[250:251], v[10:11], v[186:187], v[250:251]
	v_pk_mul_f32 v[254:255], v[204:205], v[198:199] op_sel_hi:[0,1]
	v_add_f32_e32 v14, v250, v251
	v_pk_fma_f32 v[252:253], v[8:9], v[188:189], v[252:253]
	v_pk_fma_f32 v[254:255], v[10:11], v[190:191], v[254:255]
	v_add_f32_dpp v14, v14, v14 quad_perm:[1,0,3,2] row_mask:0xf bank_mask:0xf bound_ctrl:1
	ds_read_b32 v248, v124 offset:3968
	ds_read_b128 v[228:231], v126 offset:2688
	v_add_f32_dpp v14, v14, v14 quad_perm:[2,3,0,1] row_mask:0xf bank_mask:0xf bound_ctrl:1
	ds_read_b128 v[240:243], v126 offset:3456
	ds_read_b128 v[232:235], v126 offset:2944
	v_add_f32_dpp v14, v14, v14 row_half_mirror row_mask:0xf bank_mask:0xf bound_ctrl:1
	ds_read_b128 v[244:247], v126 offset:3712
	ds_read_b128 v[236:239], v126 offset:3200
	v_add_f32_dpp v14, v14, v14 row_mirror row_mask:0xf bank_mask:0xf bound_ctrl:1
	v_pk_fma_f32 v[8:9], v[14:15], v[192:193], v[252:253] op_sel_hi:[0,1,1]
	v_pk_fma_f32 v[10:11], v[14:15], v[194:195], v[254:255] op_sel_hi:[0,1,1]
	s_waitcnt lgkmcnt(6)
	v_pk_mul_f32 v[250:251], v[8:9], v[206:207]
	v_pk_mul_f32 v[252:253], v[226:227], v[218:219] op_sel_hi:[0,1]
	v_pk_fma_f32 v[250:251], v[10:11], v[208:209], v[250:251]
	v_pk_mul_f32 v[254:255], v[226:227], v[220:221] op_sel_hi:[0,1]
	v_add_f32_e32 v14, v250, v251
	v_pk_fma_f32 v[252:253], v[8:9], v[210:211], v[252:253]
	v_pk_fma_f32 v[254:255], v[10:11], v[212:213], v[254:255]
	v_add_f32_dpp v14, v14, v14 quad_perm:[1,0,3,2] row_mask:0xf bank_mask:0xf bound_ctrl:1
	v_pk_mul_f32 v[12:13], v[8:9], v[200:201]
	ds_read_b32 v204, v124 offset:5312
	v_add_f32_dpp v14, v14, v14 quad_perm:[2,3,0,1] row_mask:0xf bank_mask:0xf bound_ctrl:1
	v_pk_fma_f32 v[12:13], v[10:11], v[202:203], v[12:13]
	ds_read_b128 v[184:187], v126 offset:4032
	v_add_f32_dpp v14, v14, v14 row_half_mirror row_mask:0xf bank_mask:0xf bound_ctrl:1
	v_add_f32_e32 v18, v12, v13
	ds_read_b128 v[196:199], v126 offset:4800
	v_add_f32_dpp v14, v14, v14 row_mirror row_mask:0xf bank_mask:0xf bound_ctrl:1
	v_pk_fma_f32 v[8:9], v[14:15], v[214:215], v[252:253] op_sel_hi:[0,1,1]
	v_pk_fma_f32 v[10:11], v[14:15], v[216:217], v[254:255] op_sel_hi:[0,1,1]
	ds_read_b128 v[188:191], v126 offset:4288
	ds_read_b128 v[200:203], v126 offset:5056
	ds_read_b128 v[192:195], v126 offset:4544
	s_waitcnt lgkmcnt(6)
	v_pk_mul_f32 v[250:251], v[8:9], v[228:229]
	v_pk_mul_f32 v[252:253], v[248:249], v[240:241] op_sel_hi:[0,1]
	v_pk_fma_f32 v[250:251], v[10:11], v[230:231], v[250:251]
	v_pk_mul_f32 v[254:255], v[248:249], v[242:243] op_sel_hi:[0,1]
	v_add_f32_e32 v14, v250, v251
	v_pk_fma_f32 v[252:253], v[8:9], v[232:233], v[252:253]
	v_pk_fma_f32 v[254:255], v[10:11], v[234:235], v[254:255]
	v_add_f32_dpp v14, v14, v14 quad_perm:[1,0,3,2] row_mask:0xf bank_mask:0xf bound_ctrl:1
	v_pk_mul_f32 v[12:13], v[8:9], v[222:223]
	ds_read_b32 v226, v124 offset:6656
	v_add_f32_dpp v14, v14, v14 quad_perm:[2,3,0,1] row_mask:0xf bank_mask:0xf bound_ctrl:1
	v_pk_fma_f32 v[12:13], v[10:11], v[224:225], v[12:13]
	ds_read_b128 v[206:209], v126 offset:5376
	v_add_f32_dpp v14, v14, v14 row_half_mirror row_mask:0xf bank_mask:0xf bound_ctrl:1
	v_add_f32_e32 v19, v12, v13
	ds_read_b128 v[218:221], v126 offset:6144
	v_add_f32_dpp v14, v14, v14 row_mirror row_mask:0xf bank_mask:0xf bound_ctrl:1
	v_pk_fma_f32 v[8:9], v[14:15], v[236:237], v[252:253] op_sel_hi:[0,1,1]
	v_pk_fma_f32 v[10:11], v[14:15], v[238:239], v[254:255] op_sel_hi:[0,1,1]
	ds_read_b128 v[210:213], v126 offset:5632
	ds_read_b128 v[222:225], v126 offset:6400
	ds_read_b128 v[214:217], v126 offset:5888
	s_waitcnt lgkmcnt(6)
	v_pk_mul_f32 v[250:251], v[8:9], v[184:185]
	v_pk_mul_f32 v[252:253], v[204:205], v[196:197] op_sel_hi:[0,1]
	v_pk_fma_f32 v[250:251], v[10:11], v[186:187], v[250:251]
	v_pk_mul_f32 v[254:255], v[204:205], v[198:199] op_sel_hi:[0,1]
	v_add_f32_e32 v14, v250, v251
	v_pk_fma_f32 v[252:253], v[8:9], v[188:189], v[252:253]
	v_pk_fma_f32 v[254:255], v[10:11], v[190:191], v[254:255]
	v_add_f32_dpp v14, v14, v14 quad_perm:[1,0,3,2] row_mask:0xf bank_mask:0xf bound_ctrl:1
	v_pk_mul_f32 v[12:13], v[8:9], v[244:245]
	ds_read_b32 v248, v124 offset:8000
	v_add_f32_dpp v14, v14, v14 quad_perm:[2,3,0,1] row_mask:0xf bank_mask:0xf bound_ctrl:1
	v_pk_fma_f32 v[12:13], v[10:11], v[246:247], v[12:13]
	ds_read_b128 v[228:231], v126 offset:6720
	v_add_f32_dpp v14, v14, v14 row_half_mirror row_mask:0xf bank_mask:0xf bound_ctrl:1
	v_add_f32_e32 v20, v12, v13
	ds_read_b128 v[240:243], v126 offset:7488
	v_add_f32_dpp v14, v14, v14 row_mirror row_mask:0xf bank_mask:0xf bound_ctrl:1
	v_pk_fma_f32 v[8:9], v[14:15], v[192:193], v[252:253] op_sel_hi:[0,1,1]
	v_pk_fma_f32 v[10:11], v[14:15], v[194:195], v[254:255] op_sel_hi:[0,1,1]
	ds_read_b128 v[232:235], v126 offset:6976
	ds_read_b128 v[244:247], v126 offset:7744
	ds_read_b128 v[236:239], v126 offset:7232
	s_waitcnt lgkmcnt(6)
	v_pk_mul_f32 v[250:251], v[8:9], v[206:207]
	v_pk_mul_f32 v[252:253], v[226:227], v[218:219] op_sel_hi:[0,1]
	v_pk_fma_f32 v[250:251], v[10:11], v[208:209], v[250:251]
	v_pk_mul_f32 v[254:255], v[226:227], v[220:221] op_sel_hi:[0,1]
	v_add_f32_e32 v14, v250, v251
	v_pk_fma_f32 v[252:253], v[8:9], v[210:211], v[252:253]
	v_pk_fma_f32 v[254:255], v[10:11], v[212:213], v[254:255]
	v_add_f32_dpp v14, v14, v14 quad_perm:[1,0,3,2] row_mask:0xf bank_mask:0xf bound_ctrl:1
	v_pk_mul_f32 v[12:13], v[8:9], v[200:201]
	ds_read_b32 v204, v124 offset:9344
	v_add_f32_dpp v14, v14, v14 quad_perm:[2,3,0,1] row_mask:0xf bank_mask:0xf bound_ctrl:1
	v_pk_fma_f32 v[12:13], v[10:11], v[202:203], v[12:13]
	ds_read_b128 v[184:187], v126 offset:8064
	v_add_f32_dpp v14, v14, v14 row_half_mirror row_mask:0xf bank_mask:0xf bound_ctrl:1
	v_add_f32_e32 v21, v12, v13
	ds_read_b128 v[196:199], v126 offset:8832
	v_add_f32_dpp v14, v14, v14 row_mirror row_mask:0xf bank_mask:0xf bound_ctrl:1
	v_pk_fma_f32 v[8:9], v[14:15], v[214:215], v[252:253] op_sel_hi:[0,1,1]
	v_pk_fma_f32 v[10:11], v[14:15], v[216:217], v[254:255] op_sel_hi:[0,1,1]
	ds_read_b128 v[188:191], v126 offset:8320
	ds_read_b128 v[200:203], v126 offset:9088
	ds_read_b128 v[192:195], v126 offset:8576
	s_waitcnt lgkmcnt(6)
	v_pk_mul_f32 v[250:251], v[8:9], v[228:229]
	v_pk_mul_f32 v[252:253], v[248:249], v[240:241] op_sel_hi:[0,1]
	v_pk_fma_f32 v[250:251], v[10:11], v[230:231], v[250:251]
	v_pk_mul_f32 v[254:255], v[248:249], v[242:243] op_sel_hi:[0,1]
	v_add_f32_e32 v14, v250, v251
	v_pk_fma_f32 v[252:253], v[8:9], v[232:233], v[252:253]
	v_pk_fma_f32 v[254:255], v[10:11], v[234:235], v[254:255]
	v_add_f32_dpp v14, v14, v14 quad_perm:[1,0,3,2] row_mask:0xf bank_mask:0xf bound_ctrl:1
	v_pk_mul_f32 v[12:13], v[8:9], v[222:223]
	ds_read_b32 v226, v124 offset:10688
	v_add_f32_dpp v14, v14, v14 quad_perm:[2,3,0,1] row_mask:0xf bank_mask:0xf bound_ctrl:1
	v_pk_fma_f32 v[12:13], v[10:11], v[224:225], v[12:13]
	ds_read_b128 v[206:209], v126 offset:9408
	v_add_f32_dpp v14, v14, v14 row_half_mirror row_mask:0xf bank_mask:0xf bound_ctrl:1
	v_add_f32_e32 v22, v12, v13
	ds_read_b128 v[218:221], v126 offset:10176
	v_add_f32_dpp v14, v14, v14 row_mirror row_mask:0xf bank_mask:0xf bound_ctrl:1
	v_pk_fma_f32 v[8:9], v[14:15], v[236:237], v[252:253] op_sel_hi:[0,1,1]
	v_pk_fma_f32 v[10:11], v[14:15], v[238:239], v[254:255] op_sel_hi:[0,1,1]
	ds_read_b128 v[210:213], v126 offset:9664
	ds_read_b128 v[222:225], v126 offset:10432
	ds_read_b128 v[214:217], v126 offset:9920
	s_waitcnt lgkmcnt(6)
	v_pk_mul_f32 v[250:251], v[8:9], v[184:185]
	v_pk_mul_f32 v[252:253], v[204:205], v[196:197] op_sel_hi:[0,1]
	v_pk_fma_f32 v[250:251], v[10:11], v[186:187], v[250:251]
	v_pk_mul_f32 v[254:255], v[204:205], v[198:199] op_sel_hi:[0,1]
	v_add_f32_e32 v14, v250, v251
	v_pk_fma_f32 v[252:253], v[8:9], v[188:189], v[252:253]
	v_pk_fma_f32 v[254:255], v[10:11], v[190:191], v[254:255]
	v_add_f32_dpp v14, v14, v14 quad_perm:[1,0,3,2] row_mask:0xf bank_mask:0xf bound_ctrl:1
	v_pk_mul_f32 v[12:13], v[8:9], v[244:245]
	ds_read_b32 v248, v124 offset:12032
	v_add_f32_dpp v14, v14, v14 quad_perm:[2,3,0,1] row_mask:0xf bank_mask:0xf bound_ctrl:1
	v_pk_fma_f32 v[12:13], v[10:11], v[246:247], v[12:13]
	ds_read_b128 v[228:231], v126 offset:10752
	v_add_f32_dpp v14, v14, v14 row_half_mirror row_mask:0xf bank_mask:0xf bound_ctrl:1
	v_add_f32_e32 v23, v12, v13
	ds_read_b128 v[240:243], v126 offset:11520
	v_add_f32_dpp v14, v14, v14 row_mirror row_mask:0xf bank_mask:0xf bound_ctrl:1
	v_pk_fma_f32 v[8:9], v[14:15], v[192:193], v[252:253] op_sel_hi:[0,1,1]
	v_pk_fma_f32 v[10:11], v[14:15], v[194:195], v[254:255] op_sel_hi:[0,1,1]
	ds_read_b128 v[232:235], v126 offset:11008
	ds_read_b128 v[244:247], v126 offset:11776
	ds_read_b128 v[236:239], v126 offset:11264
	s_waitcnt lgkmcnt(6)
	v_pk_mul_f32 v[250:251], v[8:9], v[206:207]
	v_pk_mul_f32 v[252:253], v[226:227], v[218:219] op_sel_hi:[0,1]
	v_pk_fma_f32 v[250:251], v[10:11], v[208:209], v[250:251]
	v_pk_mul_f32 v[254:255], v[226:227], v[220:221] op_sel_hi:[0,1]
	v_add_f32_e32 v14, v250, v251
	v_pk_fma_f32 v[252:253], v[8:9], v[210:211], v[252:253]
	v_pk_fma_f32 v[254:255], v[10:11], v[212:213], v[254:255]
	v_add_f32_dpp v14, v14, v14 quad_perm:[1,0,3,2] row_mask:0xf bank_mask:0xf bound_ctrl:1
	v_pk_mul_f32 v[12:13], v[8:9], v[200:201]
	ds_read_b32 v204, v124 offset:13376
	v_add_f32_dpp v14, v14, v14 quad_perm:[2,3,0,1] row_mask:0xf bank_mask:0xf bound_ctrl:1
	v_pk_fma_f32 v[12:13], v[10:11], v[202:203], v[12:13]
	ds_read_b128 v[184:187], v126 offset:12096
	v_add_f32_dpp v14, v14, v14 row_half_mirror row_mask:0xf bank_mask:0xf bound_ctrl:1
	v_add_f32_e32 v24, v12, v13
	ds_read_b128 v[196:199], v126 offset:12864
	v_add_f32_dpp v14, v14, v14 row_mirror row_mask:0xf bank_mask:0xf bound_ctrl:1
	v_pk_fma_f32 v[8:9], v[14:15], v[214:215], v[252:253] op_sel_hi:[0,1,1]
	v_pk_fma_f32 v[10:11], v[14:15], v[216:217], v[254:255] op_sel_hi:[0,1,1]
	ds_read_b128 v[188:191], v126 offset:12352
	ds_read_b128 v[200:203], v126 offset:13120
	ds_read_b128 v[192:195], v126 offset:12608
	s_waitcnt lgkmcnt(6)
	v_pk_mul_f32 v[250:251], v[8:9], v[228:229]
	v_pk_mul_f32 v[252:253], v[248:249], v[240:241] op_sel_hi:[0,1]
	v_pk_fma_f32 v[250:251], v[10:11], v[230:231], v[250:251]
	v_pk_mul_f32 v[254:255], v[248:249], v[242:243] op_sel_hi:[0,1]
	v_add_f32_e32 v14, v250, v251
	v_pk_fma_f32 v[252:253], v[8:9], v[232:233], v[252:253]
	v_pk_fma_f32 v[254:255], v[10:11], v[234:235], v[254:255]
	v_add_f32_dpp v14, v14, v14 quad_perm:[1,0,3,2] row_mask:0xf bank_mask:0xf bound_ctrl:1
	v_pk_mul_f32 v[12:13], v[8:9], v[222:223]
	ds_read_b32 v226, v124 offset:14720
	v_add_f32_dpp v14, v14, v14 quad_perm:[2,3,0,1] row_mask:0xf bank_mask:0xf bound_ctrl:1
	v_pk_fma_f32 v[12:13], v[10:11], v[224:225], v[12:13]
	ds_read_b128 v[206:209], v126 offset:13440
	v_add_f32_dpp v14, v14, v14 row_half_mirror row_mask:0xf bank_mask:0xf bound_ctrl:1
	v_add_f32_e32 v25, v12, v13
	ds_read_b128 v[218:221], v126 offset:14208
	v_add_f32_dpp v14, v14, v14 row_mirror row_mask:0xf bank_mask:0xf bound_ctrl:1
	v_pk_fma_f32 v[8:9], v[14:15], v[236:237], v[252:253] op_sel_hi:[0,1,1]
	v_pk_fma_f32 v[10:11], v[14:15], v[238:239], v[254:255] op_sel_hi:[0,1,1]
	ds_read_b128 v[210:213], v126 offset:13696
	ds_read_b128 v[222:225], v126 offset:14464
	ds_read_b128 v[214:217], v126 offset:13952
	s_waitcnt vmcnt(0)
	s_xor_b32 s0, s11, 1
	s_mulk_i32 s0, 0x5400
	v_add_u32_e32 v82, s0, v79
	v_lshlrev_b32_e32 v34, 16, v74
	v_and_b32_e32 v35, 0xffff0000, v74
	v_lshlrev_b32_e32 v36, 16, v75
	v_and_b32_e32 v37, 0xffff0000, v75
	v_lshl_add_u32 v83, v50, 2, v82
	v_pk_mul_f32 v[38:39], v[0:1], v[34:35]
	v_pk_mul_f32 v[40:41], v[2:3], v[36:37]
	v_lshlrev_b32_e32 v120, 16, v72
	v_pk_mul_f32 v[42:43], v[78:79], v[38:39] op_sel_hi:[0,1] neg_lo:[1,0] neg_hi:[1,0]
	v_pk_mul_f32 v[44:45], v[78:79], v[40:41] op_sel_hi:[0,1] neg_lo:[1,0] neg_hi:[1,0]
	v_and_b32_e32 v121, 0xffff0000, v72
	v_lshlrev_b32_e32 v122, 16, v73
	v_and_b32_e32 v123, 0xffff0000, v73
	ds_write_b128 v83, v[42:45]
	v_lshlrev_b32_e32 v38, 16, v76
	v_and_b32_e32 v39, 0xffff0000, v76
	v_lshlrev_b32_e32 v40, 16, v77
	v_and_b32_e32 v41, 0xffff0000, v77
	v_pk_add_f32 v[38:39], v[38:39], 1.0 op_sel_hi:[1,0] neg_lo:[1,0] neg_hi:[1,0]
	v_pk_add_f32 v[40:41], v[40:41], 1.0 op_sel_hi:[1,0] neg_lo:[1,0] neg_hi:[1,0]
	v_lshl_add_u32 v85, v48, 2, v82
	ds_write_b128 v83, v[38:41] offset:256
	v_pk_mul_f32 v[38:39], v[42:43], v[120:121] neg_lo:[1,0] neg_hi:[1,0]
	v_pk_mul_f32 v[40:41], v[44:45], v[122:123] neg_lo:[1,0] neg_hi:[1,0]
	v_pk_add_f32 v[120:121], v[120:121], -1.0 op_sel_hi:[1,0]
	v_pk_add_f32 v[122:123], v[122:123], -1.0 op_sel_hi:[1,0]
	ds_write_b128 v83, v[38:41] offset:512
	v_pk_fma_f32 v[120:121], v[4:5], v[120:121], 1.0 op_sel_hi:[1,1,0]
	v_pk_fma_f32 v[122:123], v[6:7], v[122:123], 1.0 op_sel_hi:[1,1,0]
	v_lshlrev_b32_e32 v42, 16, v62
	v_and_b32_e32 v43, 0xffff0000, v62
	v_pk_mul_f32 v[120:121], v[120:121], v[34:35]
	v_pk_mul_f32 v[122:123], v[122:123], v[36:37]
	v_lshlrev_b32_e32 v44, 16, v63
	v_and_b32_e32 v45, 0xffff0000, v63
	v_lshlrev_b32_e32 v84, 16, v102
	ds_write_b128 v83, v[120:123] offset:768
	ds_write_b128 v83, v[42:45] offset:1024
	ds_write_b32 v85, v84 offset:1280
	s_cmpk_eq_i32 s6, 0x20e0
	s_cbranch_scc1 .Lscan_pf_skip
	v_add_u32_e32 v131, v132, v131
	s_cmp_eq_u32 s10, 14
	s_cbranch_scc0 .Lscan_pf_nox
	v_mov_b32_e32 v131, v133
.Lscan_pf_nox:
	v_lshl_add_u32 v34, v131, 11, v58
	v_lshl_add_u32 v35, v131, 6, v134
	v_lshl_add_u32 v36, v131, 11, v60
	global_load_dwordx2 v[74:75], v34, s[2:3]
	global_load_dwordx2 v[62:63], v34, s[90:91]
	global_load_dwordx2 v[76:77], v34, s[24:25]
	global_load_dword v78, v35, s[74:75]
	global_load_dwordx2 v[72:73], v34, s[20:21]
	global_load_ushort v102, v36, s[100:101]
.Lscan_pf_skip:
	s_waitcnt lgkmcnt(12)
	v_pk_mul_f32 v[250:251], v[8:9], v[184:185]
	v_pk_mul_f32 v[252:253], v[204:205], v[196:197] op_sel_hi:[0,1]
	v_pk_fma_f32 v[250:251], v[10:11], v[186:187], v[250:251]
	v_pk_mul_f32 v[254:255], v[204:205], v[198:199] op_sel_hi:[0,1]
	v_add_f32_e32 v14, v250, v251
	v_pk_fma_f32 v[252:253], v[8:9], v[188:189], v[252:253]
	v_pk_fma_f32 v[254:255], v[10:11], v[190:191], v[254:255]
	v_add_f32_dpp v14, v14, v14 quad_perm:[1,0,3,2] row_mask:0xf bank_mask:0xf bound_ctrl:1
	v_pk_mul_f32 v[12:13], v[8:9], v[244:245]
	ds_read_b32 v248, v124 offset:16064
	v_add_f32_dpp v14, v14, v14 quad_perm:[2,3,0,1] row_mask:0xf bank_mask:0xf bound_ctrl:1
	v_pk_fma_f32 v[12:13], v[10:11], v[246:247], v[12:13]
	ds_read_b128 v[228:231], v126 offset:14784
	v_add_f32_dpp v14, v14, v14 row_half_mirror row_mask:0xf bank_mask:0xf bound_ctrl:1
	v_add_f32_e32 v26, v12, v13
	ds_read_b128 v[240:243], v126 offset:15552
	v_add_f32_dpp v14, v14, v14 row_mirror row_mask:0xf bank_mask:0xf bound_ctrl:1
	v_pk_fma_f32 v[8:9], v[14:15], v[192:193], v[252:253] op_sel_hi:[0,1,1]
	v_pk_fma_f32 v[10:11], v[14:15], v[194:195], v[254:255] op_sel_hi:[0,1,1]
	ds_read_b128 v[232:235], v126 offset:15040
	ds_read_b128 v[244:247], v126 offset:15808
	ds_read_b128 v[236:239], v126 offset:15296
	s_waitcnt lgkmcnt(12)
	v_pk_mul_f32 v[250:251], v[8:9], v[206:207]
	v_pk_mul_f32 v[252:253], v[226:227], v[218:219] op_sel_hi:[0,1]
	v_pk_fma_f32 v[250:251], v[10:11], v[208:209], v[250:251]
	v_pk_mul_f32 v[254:255], v[226:227], v[220:221] op_sel_hi:[0,1]
	v_add_f32_e32 v14, v250, v251
	v_pk_fma_f32 v[252:253], v[8:9], v[210:211], v[252:253]
	v_pk_fma_f32 v[254:255], v[10:11], v[212:213], v[254:255]
	v_add_f32_dpp v14, v14, v14 quad_perm:[1,0,3,2] row_mask:0xf bank_mask:0xf bound_ctrl:1
	v_pk_mul_f32 v[12:13], v[8:9], v[200:201]
	ds_read_b32 v204, v124 offset:17408
	v_add_f32_dpp v14, v14, v14 quad_perm:[2,3,0,1] row_mask:0xf bank_mask:0xf bound_ctrl:1
	v_pk_fma_f32 v[12:13], v[10:11], v[202:203], v[12:13]
	ds_read_b128 v[184:187], v126 offset:16128
	v_add_f32_dpp v14, v14, v14 row_half_mirror row_mask:0xf bank_mask:0xf bound_ctrl:1
	v_add_f32_e32 v27, v12, v13
	ds_read_b128 v[196:199], v126 offset:16896
	v_add_f32_dpp v14, v14, v14 row_mirror row_mask:0xf bank_mask:0xf bound_ctrl:1
	v_pk_fma_f32 v[8:9], v[14:15], v[214:215], v[252:253] op_sel_hi:[0,1,1]
	v_pk_fma_f32 v[10:11], v[14:15], v[216:217], v[254:255] op_sel_hi:[0,1,1]
	ds_read_b128 v[188:191], v126 offset:16384
	ds_read_b128 v[200:203], v126 offset:17152
	ds_read_b128 v[192:195], v126 offset:16640
	s_waitcnt lgkmcnt(6)
	v_pk_mul_f32 v[250:251], v[8:9], v[228:229]
	v_pk_mul_f32 v[252:253], v[248:249], v[240:241] op_sel_hi:[0,1]
	v_pk_fma_f32 v[250:251], v[10:11], v[230:231], v[250:251]
	v_pk_mul_f32 v[254:255], v[248:249], v[242:243] op_sel_hi:[0,1]
	v_add_f32_e32 v14, v250, v251
	v_pk_fma_f32 v[252:253], v[8:9], v[232:233], v[252:253]
	v_pk_fma_f32 v[254:255], v[10:11], v[234:235], v[254:255]
	v_add_f32_dpp v14, v14, v14 quad_perm:[1,0,3,2] row_mask:0xf bank_mask:0xf bound_ctrl:1
	v_pk_mul_f32 v[12:13], v[8:9], v[222:223]
	ds_read_b32 v226, v124 offset:18752
	v_add_f32_dpp v14, v14, v14 quad_perm:[2,3,0,1] row_mask:0xf bank_mask:0xf bound_ctrl:1
	v_pk_fma_f32 v[12:13], v[10:11], v[224:225], v[12:13]
	ds_read_b128 v[206:209], v126 offset:17472
	v_add_f32_dpp v14, v14, v14 row_half_mirror row_mask:0xf bank_mask:0xf bound_ctrl:1
	v_add_f32_e32 v28, v12, v13
	ds_read_b128 v[218:221], v126 offset:18240
	v_add_f32_dpp v14, v14, v14 row_mirror row_mask:0xf bank_mask:0xf bound_ctrl:1
	v_pk_fma_f32 v[8:9], v[14:15], v[236:237], v[252:253] op_sel_hi:[0,1,1]
	v_pk_fma_f32 v[10:11], v[14:15], v[238:239], v[254:255] op_sel_hi:[0,1,1]
	ds_read_b128 v[210:213], v126 offset:17728
	ds_read_b128 v[222:225], v126 offset:18496
	ds_read_b128 v[214:217], v126 offset:17984
	s_waitcnt lgkmcnt(6)
	v_pk_mul_f32 v[250:251], v[8:9], v[184:185]
	v_pk_mul_f32 v[252:253], v[204:205], v[196:197] op_sel_hi:[0,1]
	v_pk_fma_f32 v[250:251], v[10:11], v[186:187], v[250:251]
	v_pk_mul_f32 v[254:255], v[204:205], v[198:199] op_sel_hi:[0,1]
	v_add_f32_e32 v14, v250, v251
	v_pk_fma_f32 v[252:253], v[8:9], v[188:189], v[252:253]
	v_pk_fma_f32 v[254:255], v[10:11], v[190:191], v[254:255]
	v_add_f32_dpp v14, v14, v14 quad_perm:[1,0,3,2] row_mask:0xf bank_mask:0xf bound_ctrl:1
	v_pk_mul_f32 v[12:13], v[8:9], v[244:245]
	ds_read_b32 v248, v124 offset:20096
	v_add_f32_dpp v14, v14, v14 quad_perm:[2,3,0,1] row_mask:0xf bank_mask:0xf bound_ctrl:1
	v_pk_fma_f32 v[12:13], v[10:11], v[246:247], v[12:13]
	ds_read_b128 v[228:231], v126 offset:18816
	v_add_f32_dpp v14, v14, v14 row_half_mirror row_mask:0xf bank_mask:0xf bound_ctrl:1
	v_add_f32_e32 v29, v12, v13
	ds_read_b128 v[240:243], v126 offset:19584
	v_add_f32_dpp v14, v14, v14 row_mirror row_mask:0xf bank_mask:0xf bound_ctrl:1
	v_pk_fma_f32 v[8:9], v[14:15], v[192:193], v[252:253] op_sel_hi:[0,1,1]
	v_pk_fma_f32 v[10:11], v[14:15], v[194:195], v[254:255] op_sel_hi:[0,1,1]
	ds_read_b128 v[232:235], v126 offset:19072
	ds_read_b128 v[244:247], v126 offset:19840
	ds_read_b128 v[236:239], v126 offset:19328
	s_waitcnt lgkmcnt(6)
	v_pk_mul_f32 v[250:251], v[8:9], v[206:207]
	v_pk_mul_f32 v[252:253], v[226:227], v[218:219] op_sel_hi:[0,1]
	v_pk_fma_f32 v[250:251], v[10:11], v[208:209], v[250:251]
	v_pk_mul_f32 v[254:255], v[226:227], v[220:221] op_sel_hi:[0,1]
	v_add_f32_e32 v14, v250, v251
	v_pk_fma_f32 v[252:253], v[8:9], v[210:211], v[252:253]
	v_pk_fma_f32 v[254:255], v[10:11], v[212:213], v[254:255]
	v_add_f32_dpp v14, v14, v14 quad_perm:[1,0,3,2] row_mask:0xf bank_mask:0xf bound_ctrl:1
	v_pk_mul_f32 v[12:13], v[8:9], v[200:201]
	ds_read_b32 v204, v124 offset:21440
	v_add_f32_dpp v14, v14, v14 quad_perm:[2,3,0,1] row_mask:0xf bank_mask:0xf bound_ctrl:1
	v_pk_fma_f32 v[12:13], v[10:11], v[202:203], v[12:13]
	ds_read_b128 v[184:187], v126 offset:20160
	v_add_f32_dpp v14, v14, v14 row_half_mirror row_mask:0xf bank_mask:0xf bound_ctrl:1
	v_add_f32_e32 v30, v12, v13
	ds_read_b128 v[196:199], v126 offset:20928
	v_add_f32_dpp v14, v14, v14 row_mirror row_mask:0xf bank_mask:0xf bound_ctrl:1
	v_pk_fma_f32 v[8:9], v[14:15], v[214:215], v[252:253] op_sel_hi:[0,1,1]
	v_pk_fma_f32 v[10:11], v[14:15], v[216:217], v[254:255] op_sel_hi:[0,1,1]
	ds_read_b128 v[188:191], v126 offset:20416
	ds_read_b128 v[200:203], v126 offset:21184
	ds_read_b128 v[192:195], v126 offset:20672
	s_waitcnt lgkmcnt(6)
	v_pk_mul_f32 v[250:251], v[8:9], v[228:229]
	v_pk_mul_f32 v[252:253], v[248:249], v[240:241] op_sel_hi:[0,1]
	v_pk_fma_f32 v[250:251], v[10:11], v[230:231], v[250:251]
	v_pk_mul_f32 v[254:255], v[248:249], v[242:243] op_sel_hi:[0,1]
	v_add_f32_e32 v14, v250, v251
	v_pk_fma_f32 v[252:253], v[8:9], v[232:233], v[252:253]
	v_pk_fma_f32 v[254:255], v[10:11], v[234:235], v[254:255]
	v_add_f32_dpp v14, v14, v14 quad_perm:[1,0,3,2] row_mask:0xf bank_mask:0xf bound_ctrl:1
	v_pk_mul_f32 v[12:13], v[8:9], v[222:223]
	s_nop 0
	v_add_f32_dpp v14, v14, v14 quad_perm:[2,3,0,1] row_mask:0xf bank_mask:0xf bound_ctrl:1
	v_pk_fma_f32 v[12:13], v[10:11], v[224:225], v[12:13]
	s_nop 0
	v_add_f32_dpp v14, v14, v14 row_half_mirror row_mask:0xf bank_mask:0xf bound_ctrl:1
	v_add_f32_e32 v31, v12, v13
	s_nop 0
	v_add_f32_dpp v14, v14, v14 row_mirror row_mask:0xf bank_mask:0xf bound_ctrl:1
	v_pk_fma_f32 v[8:9], v[14:15], v[236:237], v[252:253] op_sel_hi:[0,1,1]
	v_pk_fma_f32 v[10:11], v[14:15], v[238:239], v[254:255] op_sel_hi:[0,1,1]
	s_waitcnt lgkmcnt(0)
	v_pk_mul_f32 v[250:251], v[8:9], v[184:185]
	v_pk_mul_f32 v[252:253], v[204:205], v[196:197] op_sel_hi:[0,1]
	v_pk_fma_f32 v[250:251], v[10:11], v[186:187], v[250:251]
	v_pk_mul_f32 v[254:255], v[204:205], v[198:199] op_sel_hi:[0,1]
	v_add_f32_e32 v14, v250, v251
	v_pk_fma_f32 v[252:253], v[8:9], v[188:189], v[252:253]
	v_pk_fma_f32 v[254:255], v[10:11], v[190:191], v[254:255]
	v_add_f32_dpp v14, v14, v14 quad_perm:[1,0,3,2] row_mask:0xf bank_mask:0xf bound_ctrl:1
	v_pk_mul_f32 v[12:13], v[8:9], v[244:245]
	s_nop 0
	v_add_f32_dpp v14, v14, v14 quad_perm:[2,3,0,1] row_mask:0xf bank_mask:0xf bound_ctrl:1
	v_pk_fma_f32 v[12:13], v[10:11], v[246:247], v[12:13]
	s_nop 0
	v_add_f32_dpp v14, v14, v14 row_half_mirror row_mask:0xf bank_mask:0xf bound_ctrl:1
	v_add_f32_e32 v32, v12, v13
	s_nop 0
	v_add_f32_dpp v14, v14, v14 row_mirror row_mask:0xf bank_mask:0xf bound_ctrl:1
	v_pk_fma_f32 v[8:9], v[14:15], v[192:193], v[252:253] op_sel_hi:[0,1,1]
	v_pk_fma_f32 v[10:11], v[14:15], v[194:195], v[254:255] op_sel_hi:[0,1,1]
	v_pk_mul_f32 v[12:13], v[8:9], v[200:201]
	v_add_f32_dpp v34, v18, v18 row_mirror row_mask:0xf bank_mask:0x3 bound_ctrl:1
	v_pk_fma_f32 v[12:13], v[10:11], v[202:203], v[12:13]
	v_add_f32_dpp v35, v19, v19 row_mirror row_mask:0xf bank_mask:0x3 bound_ctrl:1
	v_add_f32_dpp v36, v20, v20 row_mirror row_mask:0xf bank_mask:0x3 bound_ctrl:1
	v_add_f32_e32 v33, v12, v13
	v_add_f32_dpp v37, v21, v21 row_mirror row_mask:0xf bank_mask:0x3 bound_ctrl:1
	v_add_f32_dpp v38, v22, v22 row_mirror row_mask:0xf bank_mask:0x3 bound_ctrl:1
	v_add_f32_dpp v39, v23, v23 row_mirror row_mask:0xf bank_mask:0x3 bound_ctrl:1
	v_add_f32_dpp v40, v24, v24 row_mirror row_mask:0xf bank_mask:0x3 bound_ctrl:1
	v_add_f32_dpp v41, v25, v25 row_mirror row_mask:0xf bank_mask:0x3 bound_ctrl:1
	v_add_f32_dpp v34, v26, v26 row_mirror row_mask:0xf bank_mask:0xc bound_ctrl:1
	v_add_f32_dpp v35, v27, v27 row_mirror row_mask:0xf bank_mask:0xc bound_ctrl:1
	v_add_f32_dpp v36, v28, v28 row_mirror row_mask:0xf bank_mask:0xc bound_ctrl:1
	v_add_f32_dpp v37, v29, v29 row_mirror row_mask:0xf bank_mask:0xc bound_ctrl:1
	v_add_f32_dpp v38, v30, v30 row_mirror row_mask:0xf bank_mask:0xc bound_ctrl:1
	v_add_f32_dpp v39, v31, v31 row_mirror row_mask:0xf bank_mask:0xc bound_ctrl:1
	v_add_f32_dpp v40, v32, v32 row_mirror row_mask:0xf bank_mask:0xc bound_ctrl:1
	v_add_f32_dpp v41, v33, v33 row_mirror row_mask:0xf bank_mask:0xc bound_ctrl:1
	v_add_f32_dpp v42, v34, v34 row_half_mirror row_mask:0xf bank_mask:0x5 bound_ctrl:1
	v_add_f32_dpp v43, v35, v35 row_half_mirror row_mask:0xf bank_mask:0x5 bound_ctrl:1
	v_add_f32_dpp v44, v36, v36 row_half_mirror row_mask:0xf bank_mask:0x5 bound_ctrl:1
	v_add_f32_dpp v45, v37, v37 row_half_mirror row_mask:0xf bank_mask:0x5 bound_ctrl:1
	v_add_f32_dpp v42, v38, v38 row_half_mirror row_mask:0xf bank_mask:0xa bound_ctrl:1
	v_add_f32_dpp v43, v39, v39 row_half_mirror row_mask:0xf bank_mask:0xa bound_ctrl:1
	v_add_f32_dpp v44, v40, v40 row_half_mirror row_mask:0xf bank_mask:0xa bound_ctrl:1
	v_add_f32_dpp v45, v41, v41 row_half_mirror row_mask:0xf bank_mask:0xa bound_ctrl:1
	v_cndmask_b32_e64 v80, v44, v42, s[42:43]
	v_cndmask_b32_e64 v121, v42, v44, s[42:43]
	v_cndmask_b32_e64 v82, v45, v43, s[42:43]
	v_cndmask_b32_e64 v122, v43, v45, s[42:43]
	s_nop 0
	s_nop 0
	v_add_f32_dpp v13, v121, v80 quad_perm:[2,3,0,1] row_mask:0xf bank_mask:0xf bound_ctrl:1
	v_add_f32_dpp v14, v122, v82 quad_perm:[2,3,0,1] row_mask:0xf bank_mask:0xf bound_ctrl:1
	v_cndmask_b32_e64 v12, v13, v14, s[44:45]
	v_cndmask_b32_e64 v13, v14, v13, s[44:45]
	v_lshl_add_u32 v16, v100, 11, v99
	v_add_u32_e32 v100, v132, v100
	v_add_f32_dpp v13, v12, v13 quad_perm:[1,0,3,2] row_mask:0xf bank_mask:0xf bound_ctrl:1
	s_cmp_eq_u32 s10, 15
	s_cbranch_scc0 .Lscan_tail_nox
	v_mov_b32_e32 v100, v101
